# tile-index decode by shift/mask (row-group size is always 8) in the other seven GEMM decode sites too
# speedup vs baseline: 1.0082x; 1.0002x over previous
.LBB0_209:
	s_add_i32 s36, s36, 1
	s_mul_i32 s0, s36, s39
	s_mul_hi_u32 s1, s36, s33
	s_add_i32 s1, s1, s0
	s_mul_i32 s0, s36, s33
	s_add_u32 s18, s0, s2
	s_addc_u32 s19, s1, s30
	v_cmp_gt_i64_e32 vcc, s[18:19], v[144:145]
	v_cmp_lt_i64_e64 s[0:1], s[18:19], v[142:143]
	s_cbranch_vccnz .LBB0_211
	s_ashr_i32 s14, s18, 31
	s_lshr_b32 s14, s14, 29
	s_add_i32 s14, s18, s14
	s_ashr_i32 s15, s14, 3
	s_and_b32 s14, s14, -8
	s_sub_i32 s14, s18, s14
	s_cmp_lt_i32 s14, 0
	s_cselect_b32 s16, 49, 48
	s_mul_i32 s14, s14, s16
	s_add_i32 s14, s14, s15
	s_mul_hi_i32 s15, s14, 0x2aaaaaab
	s_lshr_b32 s16, s15, 31
	s_ashr_i32 s15, s15, 3
	s_add_i32 s15, s15, s16
	s_lshl_b32 s16, s15, 3
	s_mul_i32 s15, s15, 48
	s_sub_i32 s15, s14, s15
	s_ashr_i32 s14, s15, 3
	s_and_b32 s15, s15, 7
	s_add_i32 s16, s16, s15

.LBB0_448:
	s_ashr_i32 s18, s20, 3
	s_add_i32 s18, s22, s18
	s_ashr_i32 s19, s18, 31
	s_lshr_b32 s19, s19, 27
	s_add_i32 s19, s18, s19
	s_ashr_i32 s20, s19, 5
	s_lshl_b32 s20, s20, 3
	s_andn2_b32 s19, s19, 31
	s_sub_i32 s19, s18, s19
	s_ashr_i32 s18, s19, 3
	s_and_b32 s19, s19, 7
	s_add_i32 s20, s20, s19

.LBB0_700:
	s_ashr_i32 s16, s18, 3
	s_add_i32 s16, s29, s16
	s_ashr_i32 s17, s16, 31
	s_lshr_b32 s17, s17, 27
	s_add_i32 s17, s16, s17
	s_ashr_i32 s18, s17, 5
	s_lshl_b32 s18, s18, 3
	s_andn2_b32 s17, s17, 31
	s_sub_i32 s16, s16, s17
	s_and_b32 s16, s16, 7
	s_add_i32 s29, s18, s16
	v_cmp_lt_i64_e32 vcc, s[14:15], v[128:129]
	s_mov_b64 s[16:17], -1
	s_cbranch_vccz .LBB0_693

.LBB0_727:
	s_ashr_i32 s4, s22, 3
	s_add_i32 s4, s28, s4
	s_ashr_i32 s5, s4, 31
	s_lshr_b32 s5, s5, 27
	s_add_i32 s5, s4, s5
	s_ashr_i32 s22, s5, 5
	s_lshl_b32 s22, s22, 3
	s_andn2_b32 s5, s5, 31
	s_sub_i32 s4, s4, s5
	s_ashr_i32 s45, s4, 3
	s_and_b32 s4, s4, 7
	s_add_i32 s46, s22, s4

.LBB0_1202:
	s_ashr_i32 s9, s9, 3
	s_add_i32 s9, s35, s9
	s_ashr_i32 s30, s9, 31
	s_lshr_b32 s30, s30, 27
	s_add_i32 s30, s9, s30
	s_ashr_i32 s31, s30, 5
	s_lshl_b32 s31, s31, 3
	s_andn2_b32 s30, s30, 31
	s_sub_i32 s9, s9, s30
	s_ashr_i32 s30, s9, 3
	s_and_b32 s9, s9, 7
	s_add_i32 s34, s31, s9

.LBB0_1432:
	s_ashr_i32 s12, s14, 3
	s_add_i32 s12, s27, s12
	s_ashr_i32 s13, s12, 31
	s_lshr_b32 s13, s13, 27
	s_add_i32 s13, s12, s13
	s_ashr_i32 s14, s13, 5
	s_lshl_b32 s14, s14, 3
	s_andn2_b32 s13, s13, 31
	s_sub_i32 s12, s12, s13
	s_and_b32 s12, s12, 7
	s_add_i32 s27, s14, s12
	v_cmp_lt_i64_e32 vcc, s[8:9], v[126:127]
	s_mov_b64 s[12:13], -1
	s_cbranch_vccz .LBB0_1425

.LBB0_1457:
	s_ashr_i32 s0, s14, 3
	s_add_i32 s0, s20, s0
	s_ashr_i32 s1, s0, 31
	s_lshr_b32 s1, s1, 27
	s_add_i32 s1, s0, s1
	s_ashr_i32 s14, s1, 5
	s_lshl_b32 s14, s14, 3
	s_andn2_b32 s1, s1, 31
	s_sub_i32 s0, s0, s1
	s_ashr_i32 s39, s0, 3
	s_and_b32 s0, s0, 7
	s_add_i32 s40, s14, s0
